# grid barrier: the releasing block no longer waits for its own release atomics; wave 1 waits for its own L1 invalidate
# speedup vs baseline: 1.0106x; 1.0066x over previous
.LBB0_456:
	v_readlane_b32 s25, v255, 43
	v_readlane_b32 s0, v251, 3
	s_add_i32 s24, s25, 1
	v_readlane_b32 s1, v251, 4
	v_readlane_b32 s48, v255, 11
	v_readlane_b32 s50, v255, 13
	v_readlane_b32 s52, v255, 15
	v_readlane_b32 s54, v255, 17
	v_readlane_b32 s56, v255, 19
	v_readlane_b32 s58, v255, 21
	v_readlane_b32 s60, v255, 23
	s_cmp_ge_i32 s24, s1
	s_mov_b64 s[0:1], -1
	v_readlane_b32 s42, v255, 9
	v_readlane_b32 s49, v255, 12
	v_readlane_b32 s51, v255, 14
	v_readlane_b32 s53, v255, 16
	v_readlane_b32 s55, v255, 18
	v_readlane_b32 s57, v255, 20
	v_readlane_b32 s59, v255, 22
	v_readlane_b32 s61, v255, 24
	v_readlane_b32 s43, v255, 10
	s_cbranch_scc1 .LBB0_8
	v_readlane_b32 s0, v251, 3
	v_readlane_b32 s1, v251, 4
	s_cmp_lg_u32 s25, s0
	s_mov_b64 s[0:1], -1
	s_cbranch_scc0 .LBB0_511
	s_waitcnt vmcnt(0)
	v_mov_b32_e32 v0, v208
	s_waitcnt vmcnt(0) lgkmcnt(0)
	s_barrier
	v_readfirstlane_b32 s25, v0
	s_nop 3
	s_cmp_eq_u32 s25, 64
	s_cbranch_scc0 .Lxb_noinv
	buffer_inv sc1
	s_waitcnt vmcnt(0)

.LBB0_507:
	s_or_b64 exec, exec, s[30:31]
	s_mov_b64 s[30:31], exec
	v_mbcnt_lo_u32_b32 v0, s30, 0
	v_mbcnt_hi_u32_b32 v0, s31, v0
	v_cmp_eq_u32_e32 vcc, 0, v0
	s_and_saveexec_b64 s[36:37], vcc
	s_cbranch_execz .LBB0_509
	s_bcnt1_i32_b64 s25, s[30:31]
	v_readlane_b32 s26, v254, 39
	v_mov_b32_e32 v0, s25
	v_readlane_b32 s27, v254, 40
	s_nop 4
